# GEMM k-loops: zero-fill of guarded B-row registers done only for lanes the guard excludes, skipped by a scalar test on full tiles; obsolete carry-chain nops removed
# baseline (speedup 1.0000x reference)
.LBB0_269:
	s_waitcnt vmcnt(8)
	v_lshlrev_b32_e32 v230, 16, v66
	v_and_b32_e32 v231, 0xffff0000, v66
	v_lshlrev_b32_e32 v232, 16, v70
	v_and_b32_e32 v233, 0xffff0000, v70
	v_pk_add_f32 v[232:233], v[232:233], v[230:231] neg_lo:[0,1] neg_hi:[0,1]
	v_lshlrev_b32_e32 v234, 16, v71
	v_and_b32_e32 v235, 0xffff0000, v71
	v_lshlrev_b32_e32 v236, 16, v73
	v_and_b32_e32 v237, 0xffff0000, v73
	s_cmp_gt_u32 s20, 12
	v_pk_fma_f32 v[230:231], v[232:233], v[250:251], v[230:231]
	v_lshlrev_b32_e32 v232, 16, v67
	v_and_b32_e32 v233, 0xffff0000, v67
	v_pk_add_f32 v[234:235], v[234:235], v[232:233] neg_lo:[0,1] neg_hi:[0,1]
	v_cvt_pk_bf16_f32 v230, v230, v231
	v_pk_fma_f32 v[232:233], v[234:235], v[252:253], v[232:233]
	v_lshlrev_b32_e32 v234, 16, v72
	v_cvt_pk_bf16_f32 v231, v232, v233
	v_lshlrev_b32_e32 v232, 16, v68
	v_and_b32_e32 v233, 0xffff0000, v68
	v_and_b32_e32 v235, 0xffff0000, v72
	v_pk_add_f32 v[234:235], v[234:235], v[232:233] neg_lo:[0,1] neg_hi:[0,1]
	s_nop 0
	v_pk_fma_f32 v[232:233], v[234:235], v[246:247], v[232:233]
	v_lshlrev_b32_e32 v234, 16, v69
	v_and_b32_e32 v235, 0xffff0000, v69
	v_pk_add_f32 v[236:237], v[236:237], v[234:235] neg_lo:[0,1] neg_hi:[0,1]
	v_cvt_pk_bf16_f32 v232, v232, v233
	v_pk_fma_f32 v[234:235], v[236:237], v[248:249], v[234:235]
	v_lshlrev_b32_e32 v236, 16, v89
	v_cvt_pk_bf16_f32 v233, v234, v235
	ds_write_b128 v219, v[230:233] offset:36864
	ds_write_b128 v219, v[74:77] offset:55296
	v_lshlrev_b32_e32 v230, 16, v82
	v_and_b32_e32 v231, 0xffff0000, v82
	v_lshlrev_b32_e32 v232, 16, v86
	v_and_b32_e32 v233, 0xffff0000, v86
	v_pk_add_f32 v[232:233], v[232:233], v[230:231] neg_lo:[0,1] neg_hi:[0,1]
	v_lshlrev_b32_e32 v234, 16, v87
	v_pk_fma_f32 v[230:231], v[232:233], v[250:251], v[230:231]
	v_lshlrev_b32_e32 v232, 16, v83
	v_and_b32_e32 v233, 0xffff0000, v83
	v_and_b32_e32 v235, 0xffff0000, v87
	v_pk_add_f32 v[234:235], v[234:235], v[232:233] neg_lo:[0,1] neg_hi:[0,1]
	v_cvt_pk_bf16_f32 v230, v230, v231
	v_pk_fma_f32 v[232:233], v[234:235], v[252:253], v[232:233]
	v_lshlrev_b32_e32 v234, 16, v88
	v_cvt_pk_bf16_f32 v231, v232, v233
	v_lshlrev_b32_e32 v232, 16, v84
	v_and_b32_e32 v233, 0xffff0000, v84
	v_and_b32_e32 v235, 0xffff0000, v88
	v_pk_add_f32 v[234:235], v[234:235], v[232:233] neg_lo:[0,1] neg_hi:[0,1]
	v_and_b32_e32 v237, 0xffff0000, v89
	v_pk_fma_f32 v[232:233], v[234:235], v[246:247], v[232:233]
	v_lshlrev_b32_e32 v234, 16, v85
	v_and_b32_e32 v235, 0xffff0000, v85
	v_pk_add_f32 v[236:237], v[236:237], v[234:235] neg_lo:[0,1] neg_hi:[0,1]
	v_cvt_pk_bf16_f32 v232, v232, v233
	v_pk_fma_f32 v[234:235], v[236:237], v[248:249], v[234:235]
	v_lshlrev_b32_e32 v236, 16, v97
	v_cvt_pk_bf16_f32 v233, v234, v235
	ds_write_b128 v219, v[230:233] offset:41472
	ds_write_b128 v219, v[78:81] offset:59904
	v_lshlrev_b32_e32 v230, 16, v90
	v_and_b32_e32 v231, 0xffff0000, v90
	v_lshlrev_b32_e32 v232, 16, v94
	v_and_b32_e32 v233, 0xffff0000, v94
	v_pk_add_f32 v[232:233], v[232:233], v[230:231] neg_lo:[0,1] neg_hi:[0,1]
	v_lshlrev_b32_e32 v234, 16, v95
	v_pk_fma_f32 v[230:231], v[232:233], v[250:251], v[230:231]
	v_lshlrev_b32_e32 v232, 16, v91
	v_and_b32_e32 v233, 0xffff0000, v91
	v_and_b32_e32 v235, 0xffff0000, v95
	v_pk_add_f32 v[234:235], v[234:235], v[232:233] neg_lo:[0,1] neg_hi:[0,1]
	v_cvt_pk_bf16_f32 v230, v230, v231
	v_pk_fma_f32 v[232:233], v[234:235], v[252:253], v[232:233]
	v_lshlrev_b32_e32 v234, 16, v96
	v_cvt_pk_bf16_f32 v231, v232, v233
	v_lshlrev_b32_e32 v232, 16, v92
	v_and_b32_e32 v233, 0xffff0000, v92
	v_and_b32_e32 v235, 0xffff0000, v96
	v_pk_add_f32 v[234:235], v[234:235], v[232:233] neg_lo:[0,1] neg_hi:[0,1]
	v_and_b32_e32 v237, 0xffff0000, v97
	v_pk_fma_f32 v[232:233], v[234:235], v[246:247], v[232:233]
	v_lshlrev_b32_e32 v234, 16, v93
	v_and_b32_e32 v235, 0xffff0000, v93
	v_pk_add_f32 v[236:237], v[236:237], v[234:235] neg_lo:[0,1] neg_hi:[0,1]
	v_cvt_pk_bf16_f32 v232, v232, v233
	v_pk_fma_f32 v[234:235], v[236:237], v[248:249], v[234:235]
	s_nop 0
	v_cvt_pk_bf16_f32 v233, v234, v235
	ds_write_b128 v219, v[230:233] offset:46080
	ds_write_b128 v219, v[98:101] offset:64512
	v_lshlrev_b32_e32 v230, 16, v102
	v_and_b32_e32 v231, 0xffff0000, v102
	v_lshlrev_b32_e32 v232, 16, v106
	v_and_b32_e32 v233, 0xffff0000, v106
	v_pk_add_f32 v[232:233], v[232:233], v[230:231] neg_lo:[0,1] neg_hi:[0,1]
	s_nop 0
	v_pk_fma_f32 v[166:167], v[232:233], v[250:251], v[230:231]
	v_lshlrev_b32_e32 v230, 16, v103
	v_and_b32_e32 v231, 0xffff0000, v103
	v_lshlrev_b32_e32 v232, 16, v107
	v_and_b32_e32 v233, 0xffff0000, v107
	v_pk_add_f32 v[232:233], v[232:233], v[230:231] neg_lo:[0,1] neg_hi:[0,1]
	v_cvt_pk_bf16_f32 v166, v166, v167
	v_pk_fma_f32 v[168:169], v[232:233], v[252:253], v[230:231]
	v_lshlrev_b32_e32 v230, 16, v108
	v_cvt_pk_bf16_f32 v167, v168, v169
	v_lshlrev_b32_e32 v168, 16, v104
	v_and_b32_e32 v169, 0xffff0000, v104
	v_and_b32_e32 v231, 0xffff0000, v108
	v_pk_add_f32 v[230:231], v[230:231], v[168:169] neg_lo:[0,1] neg_hi:[0,1]
	s_nop 0
	v_pk_fma_f32 v[162:163], v[230:231], v[246:247], v[168:169]
	v_lshlrev_b32_e32 v230, 16, v109
	v_cvt_pk_bf16_f32 v168, v162, v163
	v_lshlrev_b32_e32 v162, 16, v105
	v_and_b32_e32 v163, 0xffff0000, v105
	v_and_b32_e32 v231, 0xffff0000, v109
	v_pk_add_f32 v[230:231], v[230:231], v[162:163] neg_lo:[0,1] neg_hi:[0,1]
	s_nop 0
	v_pk_fma_f32 v[162:163], v[230:231], v[248:249], v[162:163]
	s_nop 0
	v_cvt_pk_bf16_f32 v169, v162, v163
	ds_write_b128 v219, v[166:169] offset:50688
	ds_write_b128 v221, v[110:113] offset:13824
	s_cbranch_scc1 .LBB0_279
	global_load_dwordx4 v[246:249], v[208:209], off offset:256
	global_load_dwordx4 v[250:253], v[208:209], off offset:240
	global_load_dwordx4 v[66:69], v206, s[84:85] offset:384
	global_load_dwordx4 v[70:73], v192, s[86:87] offset:384
	s_and_saveexec_b64 s[2:3], s[4:5]
	s_cbranch_execz .LBB0_272
	global_load_dwordx4 v[74:77], v216, s[86:87] offset:384
.LBB0_272:
	s_andn2_b64 exec, s[2:3], s[4:5]
	s_cbranch_execz .Lzf_1
	v_mov_b32_e32 v74, 0
	v_mov_b32_e32 v75, 0
	v_mov_b32_e32 v76, 0
	v_mov_b32_e32 v77, 0
.Lzf_1:
	s_mov_b64 exec, s[2:3]
	global_load_dwordx4 v[82:85], v204, s[84:85] offset:384
	global_load_dwordx4 v[86:89], v194, s[86:87] offset:384
	s_and_saveexec_b64 s[2:3], s[6:7]
	s_cbranch_execz .LBB0_274
	global_load_dwordx4 v[78:81], v214, s[86:87] offset:384
.LBB0_274:
	s_andn2_b64 exec, s[2:3], s[6:7]
	s_cbranch_execz .Lzf_2
	v_mov_b32_e32 v78, 0
	v_mov_b32_e32 v79, 0
	v_mov_b32_e32 v80, 0
	v_mov_b32_e32 v81, 0
.Lzf_2:
	s_mov_b64 exec, s[2:3]
	global_load_dwordx4 v[90:93], v202, s[84:85] offset:384
	v_mov_b32_e32 v173, v172
	global_load_dwordx4 v[94:97], v196, s[86:87] offset:384
	s_and_saveexec_b64 s[2:3], s[8:9]
	s_cbranch_execz .LBB0_276
	global_load_dwordx4 v[98:101], v212, s[86:87] offset:384
.LBB0_276:
	s_andn2_b64 exec, s[2:3], s[8:9]
	s_cbranch_execz .Lzf_3
	v_mov_b32_e32 v98, 0
	v_mov_b32_e32 v99, 0
	v_mov_b32_e32 v100, 0
	v_mov_b32_e32 v101, 0
.Lzf_3:
	s_mov_b64 exec, s[2:3]
	global_load_dwordx4 v[102:105], v200, s[84:85] offset:384
	global_load_dwordx4 v[106:109], v198, s[86:87] offset:384
	s_and_saveexec_b64 s[2:3], s[10:11]
	s_cbranch_execz .LBB0_278
	global_load_dwordx4 v[110:113], v210, s[86:87] offset:384
.LBB0_278:
	s_andn2_b64 exec, s[2:3], s[10:11]
	s_cbranch_execz .Lzf_4
	v_mov_b32_e32 v110, 0
	v_mov_b32_e32 v111, 0
	v_mov_b32_e32 v112, 0
	v_mov_b32_e32 v113, 0
.Lzf_4:
	s_mov_b64 exec, s[2:3]
.LBB0_279:
	ds_read_b128 v[162:165], v227
	ds_read_b128 v[166:169], v228 offset:18432
	ds_read_b128 v[230:233], v228 offset:23040
	s_cmp_gt_u32 s20, 13
	s_cselect_b64 s[2:3], -1, 0
	s_and_b64 vcc, exec, s[2:3]
	s_waitcnt lgkmcnt(1)
	v_mfma_f32_32x32x16_bf16 v[50:65], v[162:165], v[166:169], v[50:65]
	s_waitcnt lgkmcnt(0)
	v_mfma_f32_32x32x16_bf16 v[34:49], v[162:165], v[230:233], v[34:49]
	ds_read_b128 v[162:165], v227 offset:4608
	s_waitcnt lgkmcnt(0)
	v_mfma_f32_32x32x16_bf16 v[18:33], v[162:165], v[166:169], v[18:33]
	v_mfma_f32_32x32x16_bf16 v[2:17], v[162:165], v[230:233], v[2:17]
	ds_read_b128 v[162:165], v227 offset:32
	ds_read_b128 v[166:169], v228 offset:18464
	ds_read_b128 v[230:233], v228 offset:23072
	s_waitcnt lgkmcnt(1)
	v_mfma_f32_32x32x16_bf16 v[50:65], v[162:165], v[166:169], v[50:65]
	s_waitcnt lgkmcnt(0)
	v_mfma_f32_32x32x16_bf16 v[34:49], v[162:165], v[230:233], v[34:49]
	ds_read_b128 v[162:165], v227 offset:4640
	s_waitcnt lgkmcnt(0)
	v_mfma_f32_32x32x16_bf16 v[18:33], v[162:165], v[166:169], v[18:33]
	v_mfma_f32_32x32x16_bf16 v[2:17], v[162:165], v[230:233], v[2:17]
	ds_read_b128 v[162:165], v227 offset:64
	ds_read_b128 v[166:169], v228 offset:18496
	ds_read_b128 v[230:233], v228 offset:23104
	s_waitcnt lgkmcnt(1)
	v_mfma_f32_32x32x16_bf16 v[50:65], v[162:165], v[166:169], v[50:65]
	s_waitcnt lgkmcnt(0)
	v_mfma_f32_32x32x16_bf16 v[34:49], v[162:165], v[230:233], v[34:49]
	ds_read_b128 v[162:165], v227 offset:4672
	s_waitcnt lgkmcnt(0)
	v_mfma_f32_32x32x16_bf16 v[18:33], v[162:165], v[166:169], v[18:33]
	v_mfma_f32_32x32x16_bf16 v[2:17], v[162:165], v[230:233], v[2:17]
	ds_read_b128 v[162:165], v227 offset:96
	ds_read_b128 v[166:169], v228 offset:18528
	ds_read_b128 v[230:233], v228 offset:23136
	s_waitcnt lgkmcnt(1)
	v_mfma_f32_32x32x16_bf16 v[50:65], v[162:165], v[166:169], v[50:65]
	s_waitcnt lgkmcnt(0)
	v_mfma_f32_32x32x16_bf16 v[34:49], v[162:165], v[230:233], v[34:49]
	ds_read_b128 v[162:165], v227 offset:4704
	s_waitcnt lgkmcnt(0)
	s_barrier
	v_mfma_f32_32x32x16_bf16 v[18:33], v[162:165], v[166:169], v[18:33]
	v_mfma_f32_32x32x16_bf16 v[2:17], v[162:165], v[230:233], v[2:17]
	s_cbranch_vccnz .LBB0_268
	s_waitcnt vmcnt(8)
	v_lshlrev_b32_e32 v230, 16, v114
	v_and_b32_e32 v231, 0xffff0000, v114
	v_lshlrev_b32_e32 v232, 16, v118
	v_and_b32_e32 v233, 0xffff0000, v118
	v_pk_add_f32 v[232:233], v[232:233], v[230:231] neg_lo:[0,1] neg_hi:[0,1]
	v_lshlrev_b32_e32 v234, 16, v119
	v_and_b32_e32 v235, 0xffff0000, v119
	v_lshlrev_b32_e32 v236, 16, v121
	v_and_b32_e32 v237, 0xffff0000, v121
	s_cmp_gt_u32 s20, 11
	v_pk_fma_f32 v[230:231], v[232:233], v[250:251], v[230:231]
	v_lshlrev_b32_e32 v232, 16, v115
	v_and_b32_e32 v233, 0xffff0000, v115
	v_pk_add_f32 v[234:235], v[234:235], v[232:233] neg_lo:[0,1] neg_hi:[0,1]
	v_cvt_pk_bf16_f32 v230, v230, v231
	v_pk_fma_f32 v[232:233], v[234:235], v[252:253], v[232:233]
	v_lshlrev_b32_e32 v234, 16, v120
	v_cvt_pk_bf16_f32 v231, v232, v233
	v_lshlrev_b32_e32 v232, 16, v116
	v_and_b32_e32 v233, 0xffff0000, v116
	v_and_b32_e32 v235, 0xffff0000, v120
	v_pk_add_f32 v[234:235], v[234:235], v[232:233] neg_lo:[0,1] neg_hi:[0,1]
	s_nop 0
	v_pk_fma_f32 v[232:233], v[234:235], v[246:247], v[232:233]
	v_lshlrev_b32_e32 v234, 16, v117
	v_and_b32_e32 v235, 0xffff0000, v117
	v_pk_add_f32 v[236:237], v[236:237], v[234:235] neg_lo:[0,1] neg_hi:[0,1]
	v_cvt_pk_bf16_f32 v232, v232, v233
	v_pk_fma_f32 v[234:235], v[236:237], v[248:249], v[234:235]
	v_lshlrev_b32_e32 v236, 16, v137
	v_cvt_pk_bf16_f32 v233, v234, v235
	ds_write_b128 v219, v[230:233]
	ds_write_b128 v219, v[122:125] offset:18432
	v_lshlrev_b32_e32 v230, 16, v130
	v_and_b32_e32 v231, 0xffff0000, v130
	v_lshlrev_b32_e32 v232, 16, v134
	v_and_b32_e32 v233, 0xffff0000, v134
	v_pk_add_f32 v[232:233], v[232:233], v[230:231] neg_lo:[0,1] neg_hi:[0,1]
	v_lshlrev_b32_e32 v234, 16, v135
	v_pk_fma_f32 v[230:231], v[232:233], v[250:251], v[230:231]
	v_lshlrev_b32_e32 v232, 16, v131
	v_and_b32_e32 v233, 0xffff0000, v131
	v_and_b32_e32 v235, 0xffff0000, v135
	v_pk_add_f32 v[234:235], v[234:235], v[232:233] neg_lo:[0,1] neg_hi:[0,1]
	v_cvt_pk_bf16_f32 v230, v230, v231
	v_pk_fma_f32 v[232:233], v[234:235], v[252:253], v[232:233]
	v_lshlrev_b32_e32 v234, 16, v136
	v_cvt_pk_bf16_f32 v231, v232, v233
	v_lshlrev_b32_e32 v232, 16, v132
	v_and_b32_e32 v233, 0xffff0000, v132
	v_and_b32_e32 v235, 0xffff0000, v136
	v_pk_add_f32 v[234:235], v[234:235], v[232:233] neg_lo:[0,1] neg_hi:[0,1]
	v_and_b32_e32 v237, 0xffff0000, v137
	v_pk_fma_f32 v[232:233], v[234:235], v[246:247], v[232:233]
	v_lshlrev_b32_e32 v234, 16, v133
	v_and_b32_e32 v235, 0xffff0000, v133
	v_pk_add_f32 v[236:237], v[236:237], v[234:235] neg_lo:[0,1] neg_hi:[0,1]
	v_cvt_pk_bf16_f32 v232, v232, v233
	v_pk_fma_f32 v[234:235], v[236:237], v[248:249], v[234:235]
	v_lshlrev_b32_e32 v236, 16, v145
	v_cvt_pk_bf16_f32 v233, v234, v235
	ds_write_b128 v219, v[230:233] offset:4608
	ds_write_b128 v219, v[126:129] offset:23040
	v_lshlrev_b32_e32 v230, 16, v138
	v_and_b32_e32 v231, 0xffff0000, v138
	v_lshlrev_b32_e32 v232, 16, v142
	v_and_b32_e32 v233, 0xffff0000, v142
	v_pk_add_f32 v[232:233], v[232:233], v[230:231] neg_lo:[0,1] neg_hi:[0,1]
	v_lshlrev_b32_e32 v234, 16, v143
	v_pk_fma_f32 v[230:231], v[232:233], v[250:251], v[230:231]
	v_lshlrev_b32_e32 v232, 16, v139
	v_and_b32_e32 v233, 0xffff0000, v139
	v_and_b32_e32 v235, 0xffff0000, v143
	v_pk_add_f32 v[234:235], v[234:235], v[232:233] neg_lo:[0,1] neg_hi:[0,1]
	v_cvt_pk_bf16_f32 v230, v230, v231
	v_pk_fma_f32 v[232:233], v[234:235], v[252:253], v[232:233]
	v_lshlrev_b32_e32 v234, 16, v144
	v_cvt_pk_bf16_f32 v231, v232, v233
	v_lshlrev_b32_e32 v232, 16, v140
	v_and_b32_e32 v233, 0xffff0000, v140
	v_and_b32_e32 v235, 0xffff0000, v144
	v_pk_add_f32 v[234:235], v[234:235], v[232:233] neg_lo:[0,1] neg_hi:[0,1]
	v_and_b32_e32 v237, 0xffff0000, v145
	v_pk_fma_f32 v[232:233], v[234:235], v[246:247], v[232:233]
	v_lshlrev_b32_e32 v234, 16, v141
	v_and_b32_e32 v235, 0xffff0000, v141
	v_pk_add_f32 v[236:237], v[236:237], v[234:235] neg_lo:[0,1] neg_hi:[0,1]
	v_cvt_pk_bf16_f32 v232, v232, v233
	v_pk_fma_f32 v[234:235], v[236:237], v[248:249], v[234:235]
	s_nop 0
	v_cvt_pk_bf16_f32 v233, v234, v235
	ds_write_b128 v219, v[230:233] offset:9216
	ds_write_b128 v219, v[146:149] offset:27648
	v_lshlrev_b32_e32 v230, 16, v150
	v_and_b32_e32 v231, 0xffff0000, v150
	v_lshlrev_b32_e32 v232, 16, v154
	v_and_b32_e32 v233, 0xffff0000, v154
	v_pk_add_f32 v[232:233], v[232:233], v[230:231] neg_lo:[0,1] neg_hi:[0,1]
	s_nop 0
	v_pk_fma_f32 v[166:167], v[232:233], v[250:251], v[230:231]
	v_lshlrev_b32_e32 v230, 16, v151
	v_and_b32_e32 v231, 0xffff0000, v151
	v_lshlrev_b32_e32 v232, 16, v155
	v_and_b32_e32 v233, 0xffff0000, v155
	v_pk_add_f32 v[232:233], v[232:233], v[230:231] neg_lo:[0,1] neg_hi:[0,1]
	v_cvt_pk_bf16_f32 v166, v166, v167
	v_pk_fma_f32 v[168:169], v[232:233], v[252:253], v[230:231]
	v_lshlrev_b32_e32 v230, 16, v156
	v_cvt_pk_bf16_f32 v167, v168, v169
	v_lshlrev_b32_e32 v168, 16, v152
	v_and_b32_e32 v169, 0xffff0000, v152
	v_and_b32_e32 v231, 0xffff0000, v156
	v_pk_add_f32 v[230:231], v[230:231], v[168:169] neg_lo:[0,1] neg_hi:[0,1]
	s_nop 0
	v_pk_fma_f32 v[162:163], v[230:231], v[246:247], v[168:169]
	v_lshlrev_b32_e32 v230, 16, v157
	v_cvt_pk_bf16_f32 v168, v162, v163
	v_lshlrev_b32_e32 v162, 16, v153
	v_and_b32_e32 v163, 0xffff0000, v153
	v_and_b32_e32 v231, 0xffff0000, v157
	v_pk_add_f32 v[230:231], v[230:231], v[162:163] neg_lo:[0,1] neg_hi:[0,1]
	s_nop 0
	v_pk_fma_f32 v[162:163], v[230:231], v[248:249], v[162:163]
	s_nop 0
	v_cvt_pk_bf16_f32 v169, v162, v163
	ds_write_b128 v219, v[166:169] offset:13824
	ds_write_b128 v219, v[158:161] offset:32256
	global_load_dwordx4 v[246:249], v[208:209], off offset:512
	global_load_dwordx4 v[250:253], v[208:209], off offset:496
	s_cbranch_scc1 .Lmixpf_a_last
	global_load_dwordx4 v[114:117], v206, s[84:85] offset:512
	global_load_dwordx4 v[118:121], v192, s[86:87] offset:512
	s_and_saveexec_b64 s[28:29], s[4:5]
	s_cbranch_execz .LBB0_283
	global_load_dwordx4 v[122:125], v216, s[86:87] offset:512
.LBB0_283:
	s_andn2_b64 exec, s[28:29], s[4:5]
	s_cbranch_execz .Lzf_5
	v_mov_b32_e32 v122, 0
	v_mov_b32_e32 v123, 0
	v_mov_b32_e32 v124, 0
	v_mov_b32_e32 v125, 0
.Lzf_5:
	s_mov_b64 exec, s[28:29]
	global_load_dwordx4 v[130:133], v204, s[84:85] offset:512
	global_load_dwordx4 v[134:137], v194, s[86:87] offset:512
	s_and_saveexec_b64 s[28:29], s[6:7]
	s_cbranch_execz .LBB0_285
	global_load_dwordx4 v[126:129], v214, s[86:87] offset:512
.LBB0_285:
	s_andn2_b64 exec, s[28:29], s[6:7]
	s_cbranch_execz .Lzf_6
	v_mov_b32_e32 v126, 0
	v_mov_b32_e32 v127, 0
	v_mov_b32_e32 v128, 0
	v_mov_b32_e32 v129, 0
.Lzf_6:
	s_mov_b64 exec, s[28:29]
	global_load_dwordx4 v[138:141], v202, s[84:85] offset:512
	v_mov_b32_e32 v173, v172
	global_load_dwordx4 v[142:145], v196, s[86:87] offset:512
	s_and_saveexec_b64 s[28:29], s[8:9]
	s_cbranch_execz .LBB0_287
	global_load_dwordx4 v[146:149], v212, s[86:87] offset:512
.LBB0_287:
	s_andn2_b64 exec, s[28:29], s[8:9]
	s_cbranch_execz .Lzf_7
	v_mov_b32_e32 v146, 0
	v_mov_b32_e32 v147, 0
	v_mov_b32_e32 v148, 0
	v_mov_b32_e32 v149, 0
.Lzf_7:
	s_mov_b64 exec, s[28:29]
	global_load_dwordx4 v[150:153], v200, s[84:85] offset:512
	global_load_dwordx4 v[154:157], v198, s[86:87] offset:512
	s_and_saveexec_b64 s[28:29], s[10:11]
	s_cbranch_execz .Lzf_8
	global_load_dwordx4 v[158:161], v210, s[86:87] offset:512
.Lzf_8:
	s_andn2_b64 exec, s[28:29], s[10:11]
	s_cbranch_execz .LBB0_267
	v_mov_b32_e32 v158, 0
	v_mov_b32_e32 v159, 0
	v_mov_b32_e32 v160, 0
	v_mov_b32_e32 v161, 0
	s_branch .LBB0_267

.LBB0_675:
	s_waitcnt vmcnt(8)
	v_lshlrev_b32_e32 v234, 16, v66
	v_and_b32_e32 v235, 0xffff0000, v66
	v_lshlrev_b32_e32 v236, 16, v70
	v_and_b32_e32 v237, 0xffff0000, v70
	v_pk_add_f32 v[236:237], v[236:237], v[234:235] neg_lo:[0,1] neg_hi:[0,1]
	v_lshlrev_b32_e32 v238, 16, v71
	v_and_b32_e32 v239, 0xffff0000, v71
	v_lshlrev_b32_e32 v240, 16, v73
	v_and_b32_e32 v241, 0xffff0000, v73
	s_cmp_gt_u32 s14, 12
	v_pk_fma_f32 v[234:235], v[236:237], v[250:251], v[234:235]
	v_lshlrev_b32_e32 v236, 16, v67
	v_and_b32_e32 v237, 0xffff0000, v67
	v_pk_add_f32 v[238:239], v[238:239], v[236:237] neg_lo:[0,1] neg_hi:[0,1]
	v_cvt_pk_bf16_f32 v234, v234, v235
	v_pk_fma_f32 v[236:237], v[238:239], v[252:253], v[236:237]
	v_lshlrev_b32_e32 v238, 16, v72
	v_cvt_pk_bf16_f32 v235, v236, v237
	v_lshlrev_b32_e32 v236, 16, v68
	v_and_b32_e32 v237, 0xffff0000, v68
	v_and_b32_e32 v239, 0xffff0000, v72
	v_pk_add_f32 v[238:239], v[238:239], v[236:237] neg_lo:[0,1] neg_hi:[0,1]
	s_nop 0
	v_pk_fma_f32 v[236:237], v[238:239], v[246:247], v[236:237]
	v_lshlrev_b32_e32 v238, 16, v69
	v_and_b32_e32 v239, 0xffff0000, v69
	v_pk_add_f32 v[240:241], v[240:241], v[238:239] neg_lo:[0,1] neg_hi:[0,1]
	v_cvt_pk_bf16_f32 v236, v236, v237
	v_pk_fma_f32 v[238:239], v[240:241], v[248:249], v[238:239]
	v_lshlrev_b32_e32 v240, 16, v85
	v_cvt_pk_bf16_f32 v237, v238, v239
	ds_write_b128 v213, v[234:237] offset:36864
	ds_write_b128 v213, v[74:77] offset:55296
	v_lshlrev_b32_e32 v234, 16, v78
	v_and_b32_e32 v235, 0xffff0000, v78
	v_lshlrev_b32_e32 v236, 16, v82
	v_and_b32_e32 v237, 0xffff0000, v82
	v_pk_add_f32 v[236:237], v[236:237], v[234:235] neg_lo:[0,1] neg_hi:[0,1]
	v_lshlrev_b32_e32 v238, 16, v83
	v_pk_fma_f32 v[234:235], v[236:237], v[250:251], v[234:235]
	v_lshlrev_b32_e32 v236, 16, v79
	v_and_b32_e32 v237, 0xffff0000, v79
	v_and_b32_e32 v239, 0xffff0000, v83
	v_pk_add_f32 v[238:239], v[238:239], v[236:237] neg_lo:[0,1] neg_hi:[0,1]
	v_cvt_pk_bf16_f32 v234, v234, v235
	v_pk_fma_f32 v[236:237], v[238:239], v[252:253], v[236:237]
	v_lshlrev_b32_e32 v238, 16, v84
	v_cvt_pk_bf16_f32 v235, v236, v237
	v_lshlrev_b32_e32 v236, 16, v80
	v_and_b32_e32 v237, 0xffff0000, v80
	v_and_b32_e32 v239, 0xffff0000, v84
	v_pk_add_f32 v[238:239], v[238:239], v[236:237] neg_lo:[0,1] neg_hi:[0,1]
	v_and_b32_e32 v241, 0xffff0000, v85
	v_pk_fma_f32 v[236:237], v[238:239], v[246:247], v[236:237]
	v_lshlrev_b32_e32 v238, 16, v81
	v_and_b32_e32 v239, 0xffff0000, v81
	v_pk_add_f32 v[240:241], v[240:241], v[238:239] neg_lo:[0,1] neg_hi:[0,1]
	v_cvt_pk_bf16_f32 v236, v236, v237
	v_pk_fma_f32 v[238:239], v[240:241], v[248:249], v[238:239]
	v_lshlrev_b32_e32 v240, 16, v101
	v_cvt_pk_bf16_f32 v237, v238, v239
	ds_write_b128 v213, v[234:237] offset:41472
	ds_write_b128 v213, v[86:89] offset:59904
	v_lshlrev_b32_e32 v234, 16, v94
	v_and_b32_e32 v235, 0xffff0000, v94
	v_lshlrev_b32_e32 v236, 16, v98
	v_and_b32_e32 v237, 0xffff0000, v98
	v_pk_add_f32 v[236:237], v[236:237], v[234:235] neg_lo:[0,1] neg_hi:[0,1]
	v_lshlrev_b32_e32 v238, 16, v99
	v_pk_fma_f32 v[234:235], v[236:237], v[250:251], v[234:235]
	v_lshlrev_b32_e32 v236, 16, v95
	v_and_b32_e32 v237, 0xffff0000, v95
	v_and_b32_e32 v239, 0xffff0000, v99
	v_pk_add_f32 v[238:239], v[238:239], v[236:237] neg_lo:[0,1] neg_hi:[0,1]
	v_cvt_pk_bf16_f32 v234, v234, v235
	v_pk_fma_f32 v[236:237], v[238:239], v[252:253], v[236:237]
	v_lshlrev_b32_e32 v238, 16, v100
	v_cvt_pk_bf16_f32 v235, v236, v237
	v_lshlrev_b32_e32 v236, 16, v96
	v_and_b32_e32 v237, 0xffff0000, v96
	v_and_b32_e32 v239, 0xffff0000, v100
	v_pk_add_f32 v[238:239], v[238:239], v[236:237] neg_lo:[0,1] neg_hi:[0,1]
	v_and_b32_e32 v241, 0xffff0000, v101
	v_pk_fma_f32 v[236:237], v[238:239], v[246:247], v[236:237]
	v_lshlrev_b32_e32 v238, 16, v97
	v_and_b32_e32 v239, 0xffff0000, v97
	v_pk_add_f32 v[240:241], v[240:241], v[238:239] neg_lo:[0,1] neg_hi:[0,1]
	v_cvt_pk_bf16_f32 v236, v236, v237
	v_pk_fma_f32 v[238:239], v[240:241], v[248:249], v[238:239]
	s_nop 0
	v_cvt_pk_bf16_f32 v237, v238, v239
	ds_write_b128 v213, v[234:237] offset:46080
	ds_write_b128 v213, v[90:93] offset:64512
	v_lshlrev_b32_e32 v234, 16, v102
	v_and_b32_e32 v235, 0xffff0000, v102
	v_lshlrev_b32_e32 v236, 16, v106
	v_and_b32_e32 v237, 0xffff0000, v106
	v_pk_add_f32 v[236:237], v[236:237], v[234:235] neg_lo:[0,1] neg_hi:[0,1]
	s_nop 0
	v_pk_fma_f32 v[166:167], v[236:237], v[250:251], v[234:235]
	v_lshlrev_b32_e32 v234, 16, v103
	v_and_b32_e32 v235, 0xffff0000, v103
	v_lshlrev_b32_e32 v236, 16, v107
	v_and_b32_e32 v237, 0xffff0000, v107
	v_pk_add_f32 v[236:237], v[236:237], v[234:235] neg_lo:[0,1] neg_hi:[0,1]
	v_cvt_pk_bf16_f32 v166, v166, v167
	v_pk_fma_f32 v[168:169], v[236:237], v[252:253], v[234:235]
	v_lshlrev_b32_e32 v234, 16, v108
	v_cvt_pk_bf16_f32 v167, v168, v169
	v_lshlrev_b32_e32 v168, 16, v104
	v_and_b32_e32 v169, 0xffff0000, v104
	v_and_b32_e32 v235, 0xffff0000, v108
	v_pk_add_f32 v[234:235], v[234:235], v[168:169] neg_lo:[0,1] neg_hi:[0,1]
	s_nop 0
	v_pk_fma_f32 v[162:163], v[234:235], v[246:247], v[168:169]
	v_lshlrev_b32_e32 v234, 16, v109
	v_cvt_pk_bf16_f32 v168, v162, v163
	v_lshlrev_b32_e32 v162, 16, v105
	v_and_b32_e32 v163, 0xffff0000, v105
	v_and_b32_e32 v235, 0xffff0000, v109
	v_pk_add_f32 v[234:235], v[234:235], v[162:163] neg_lo:[0,1] neg_hi:[0,1]
	s_nop 0
	v_pk_fma_f32 v[162:163], v[234:235], v[248:249], v[162:163]
	s_nop 0
	v_cvt_pk_bf16_f32 v169, v162, v163
	ds_write_b128 v213, v[166:169] offset:50688
	ds_write_b128 v214, v[110:113] offset:13824
	s_cbranch_scc1 .LBB0_683
	global_load_dwordx4 v[246:249], v[194:195], off offset:256
	global_load_dwordx4 v[250:253], v[194:195], off offset:240
	global_load_dwordx4 v[66:69], v200, s[84:85] offset:384
	global_load_dwordx4 v[70:73], v186, s[86:87] offset:384
	global_load_dwordx4 v[74:77], v210, s[86:87] offset:-128
	global_load_dwordx4 v[78:81], v208, s[84:85] offset:384
	global_load_dwordx4 v[82:85], v188, s[86:87] offset:384
	s_and_saveexec_b64 s[2:3], s[0:1]
	s_cbranch_execz .LBB0_678
	global_load_dwordx4 v[86:89], v206, s[86:87] offset:-128
.LBB0_678:
	s_andn2_b64 exec, s[2:3], s[0:1]
	s_cbranch_execz .Lzf_9
	v_mov_b32_e32 v86, 0
	v_mov_b32_e32 v87, 0
	v_mov_b32_e32 v88, 0
	v_mov_b32_e32 v89, 0
.Lzf_9:
	s_mov_b64 exec, s[2:3]
	global_load_dwordx4 v[94:97], v204, s[84:85] offset:384
	global_load_dwordx4 v[98:101], v190, s[86:87] offset:384
	s_and_saveexec_b64 s[2:3], s[4:5]
	s_cbranch_execz .LBB0_680
	global_load_dwordx4 v[90:93], v202, s[86:87] offset:-128
.LBB0_680:
	s_andn2_b64 exec, s[2:3], s[4:5]
	s_cbranch_execz .Lzf_10
	v_mov_b32_e32 v90, 0
	v_mov_b32_e32 v91, 0
	v_mov_b32_e32 v92, 0
	v_mov_b32_e32 v93, 0
.Lzf_10:
	s_mov_b64 exec, s[2:3]
	global_load_dwordx4 v[102:105], v198, s[84:85] offset:384
	global_load_dwordx4 v[106:109], v192, s[86:87] offset:384
	s_and_saveexec_b64 s[2:3], s[6:7]
	s_cbranch_execz .LBB0_682
	global_load_dwordx4 v[110:113], v196, s[86:87] offset:-128
.LBB0_682:
	s_andn2_b64 exec, s[2:3], s[6:7]
	s_cbranch_execz .Lzf_11
	v_mov_b32_e32 v110, 0
	v_mov_b32_e32 v111, 0
	v_mov_b32_e32 v112, 0
	v_mov_b32_e32 v113, 0

.LBB0_683:
	ds_read_b128 v[162:165], v233 offset:18432
	ds_read_b128 v[166:169], v232
	ds_read_b128 v[234:237], v233 offset:23040
	s_cmp_gt_u32 s14, 13
	s_cselect_b64 s[2:3], -1, 0
	s_and_b64 vcc, exec, s[2:3]
	s_waitcnt lgkmcnt(1)
	v_mfma_f32_32x32x16_bf16 v[50:65], v[162:165], v[166:169], v[50:65]
	s_waitcnt lgkmcnt(0)
	v_mfma_f32_32x32x16_bf16 v[34:49], v[234:237], v[166:169], v[34:49]
	ds_read_b128 v[166:169], v232 offset:4608
	s_waitcnt lgkmcnt(0)
	v_mfma_f32_32x32x16_bf16 v[18:33], v[162:165], v[166:169], v[18:33]
	v_mfma_f32_32x32x16_bf16 v[2:17], v[234:237], v[166:169], v[2:17]
	ds_read_b128 v[162:165], v233 offset:18464
	ds_read_b128 v[166:169], v232 offset:32
	ds_read_b128 v[234:237], v233 offset:23072
	s_waitcnt lgkmcnt(1)
	v_mfma_f32_32x32x16_bf16 v[50:65], v[162:165], v[166:169], v[50:65]
	s_waitcnt lgkmcnt(0)
	v_mfma_f32_32x32x16_bf16 v[34:49], v[234:237], v[166:169], v[34:49]
	ds_read_b128 v[166:169], v232 offset:4640
	s_waitcnt lgkmcnt(0)
	v_mfma_f32_32x32x16_bf16 v[18:33], v[162:165], v[166:169], v[18:33]
	v_mfma_f32_32x32x16_bf16 v[2:17], v[234:237], v[166:169], v[2:17]
	ds_read_b128 v[162:165], v233 offset:18496
	ds_read_b128 v[166:169], v232 offset:64
	ds_read_b128 v[234:237], v233 offset:23104
	s_waitcnt lgkmcnt(1)
	v_mfma_f32_32x32x16_bf16 v[50:65], v[162:165], v[166:169], v[50:65]
	s_waitcnt lgkmcnt(0)
	v_mfma_f32_32x32x16_bf16 v[34:49], v[234:237], v[166:169], v[34:49]
	ds_read_b128 v[166:169], v232 offset:4672
	s_waitcnt lgkmcnt(0)
	v_mfma_f32_32x32x16_bf16 v[18:33], v[162:165], v[166:169], v[18:33]
	v_mfma_f32_32x32x16_bf16 v[2:17], v[234:237], v[166:169], v[2:17]
	ds_read_b128 v[162:165], v233 offset:18528
	ds_read_b128 v[166:169], v232 offset:96
	ds_read_b128 v[234:237], v233 offset:23136
	s_waitcnt lgkmcnt(1)
	v_mfma_f32_32x32x16_bf16 v[50:65], v[162:165], v[166:169], v[50:65]
	s_waitcnt lgkmcnt(0)
	v_mfma_f32_32x32x16_bf16 v[34:49], v[234:237], v[166:169], v[34:49]
	ds_read_b128 v[166:169], v232 offset:4704
	s_waitcnt lgkmcnt(0)
	s_barrier
	v_mfma_f32_32x32x16_bf16 v[18:33], v[162:165], v[166:169], v[18:33]
	v_mfma_f32_32x32x16_bf16 v[2:17], v[234:237], v[166:169], v[2:17]
	s_cbranch_vccnz .LBB0_674
	s_waitcnt vmcnt(8)
	v_lshlrev_b32_e32 v234, 16, v114
	v_and_b32_e32 v235, 0xffff0000, v114
	v_lshlrev_b32_e32 v236, 16, v118
	v_and_b32_e32 v237, 0xffff0000, v118
	v_pk_add_f32 v[236:237], v[236:237], v[234:235] neg_lo:[0,1] neg_hi:[0,1]
	v_lshlrev_b32_e32 v238, 16, v119
	v_and_b32_e32 v239, 0xffff0000, v119
	v_lshlrev_b32_e32 v240, 16, v121
	v_and_b32_e32 v241, 0xffff0000, v121
	s_cmp_gt_u32 s14, 11
	v_pk_fma_f32 v[234:235], v[236:237], v[250:251], v[234:235]
	v_lshlrev_b32_e32 v236, 16, v115
	v_and_b32_e32 v237, 0xffff0000, v115
	v_pk_add_f32 v[238:239], v[238:239], v[236:237] neg_lo:[0,1] neg_hi:[0,1]
	v_cvt_pk_bf16_f32 v234, v234, v235
	v_pk_fma_f32 v[236:237], v[238:239], v[252:253], v[236:237]
	v_lshlrev_b32_e32 v238, 16, v120
	v_cvt_pk_bf16_f32 v235, v236, v237
	v_lshlrev_b32_e32 v236, 16, v116
	v_and_b32_e32 v237, 0xffff0000, v116
	v_and_b32_e32 v239, 0xffff0000, v120
	v_pk_add_f32 v[238:239], v[238:239], v[236:237] neg_lo:[0,1] neg_hi:[0,1]
	s_nop 0
	v_pk_fma_f32 v[236:237], v[238:239], v[246:247], v[236:237]
	v_lshlrev_b32_e32 v238, 16, v117
	v_and_b32_e32 v239, 0xffff0000, v117
	v_pk_add_f32 v[240:241], v[240:241], v[238:239] neg_lo:[0,1] neg_hi:[0,1]
	v_cvt_pk_bf16_f32 v236, v236, v237
	v_pk_fma_f32 v[238:239], v[240:241], v[248:249], v[238:239]
	v_lshlrev_b32_e32 v240, 16, v133
	v_cvt_pk_bf16_f32 v237, v238, v239
	ds_write_b128 v213, v[234:237]
	ds_write_b128 v213, v[122:125] offset:18432
	v_lshlrev_b32_e32 v234, 16, v126
	v_and_b32_e32 v235, 0xffff0000, v126
	v_lshlrev_b32_e32 v236, 16, v130
	v_and_b32_e32 v237, 0xffff0000, v130
	v_pk_add_f32 v[236:237], v[236:237], v[234:235] neg_lo:[0,1] neg_hi:[0,1]
	v_lshlrev_b32_e32 v238, 16, v131
	v_pk_fma_f32 v[234:235], v[236:237], v[250:251], v[234:235]
	v_lshlrev_b32_e32 v236, 16, v127
	v_and_b32_e32 v237, 0xffff0000, v127
	v_and_b32_e32 v239, 0xffff0000, v131
	v_pk_add_f32 v[238:239], v[238:239], v[236:237] neg_lo:[0,1] neg_hi:[0,1]
	v_cvt_pk_bf16_f32 v234, v234, v235
	v_pk_fma_f32 v[236:237], v[238:239], v[252:253], v[236:237]
	v_lshlrev_b32_e32 v238, 16, v132
	v_cvt_pk_bf16_f32 v235, v236, v237
	v_lshlrev_b32_e32 v236, 16, v128
	v_and_b32_e32 v237, 0xffff0000, v128
	v_and_b32_e32 v239, 0xffff0000, v132
	v_pk_add_f32 v[238:239], v[238:239], v[236:237] neg_lo:[0,1] neg_hi:[0,1]
	v_and_b32_e32 v241, 0xffff0000, v133
	v_pk_fma_f32 v[236:237], v[238:239], v[246:247], v[236:237]
	v_lshlrev_b32_e32 v238, 16, v129
	v_and_b32_e32 v239, 0xffff0000, v129
	v_pk_add_f32 v[240:241], v[240:241], v[238:239] neg_lo:[0,1] neg_hi:[0,1]
	v_cvt_pk_bf16_f32 v236, v236, v237
	v_pk_fma_f32 v[238:239], v[240:241], v[248:249], v[238:239]
	v_lshlrev_b32_e32 v240, 16, v149
	v_cvt_pk_bf16_f32 v237, v238, v239
	ds_write_b128 v213, v[234:237] offset:4608
	ds_write_b128 v213, v[134:137] offset:23040
	v_lshlrev_b32_e32 v234, 16, v142
	v_and_b32_e32 v235, 0xffff0000, v142
	v_lshlrev_b32_e32 v236, 16, v146
	v_and_b32_e32 v237, 0xffff0000, v146
	v_pk_add_f32 v[236:237], v[236:237], v[234:235] neg_lo:[0,1] neg_hi:[0,1]
	v_lshlrev_b32_e32 v238, 16, v147
	v_pk_fma_f32 v[234:235], v[236:237], v[250:251], v[234:235]
	v_lshlrev_b32_e32 v236, 16, v143
	v_and_b32_e32 v237, 0xffff0000, v143
	v_and_b32_e32 v239, 0xffff0000, v147
	v_pk_add_f32 v[238:239], v[238:239], v[236:237] neg_lo:[0,1] neg_hi:[0,1]
	v_cvt_pk_bf16_f32 v234, v234, v235
	v_pk_fma_f32 v[236:237], v[238:239], v[252:253], v[236:237]
	v_lshlrev_b32_e32 v238, 16, v148
	v_cvt_pk_bf16_f32 v235, v236, v237
	v_lshlrev_b32_e32 v236, 16, v144
	v_and_b32_e32 v237, 0xffff0000, v144
	v_and_b32_e32 v239, 0xffff0000, v148
	v_pk_add_f32 v[238:239], v[238:239], v[236:237] neg_lo:[0,1] neg_hi:[0,1]
	v_and_b32_e32 v241, 0xffff0000, v149
	v_pk_fma_f32 v[236:237], v[238:239], v[246:247], v[236:237]
	v_lshlrev_b32_e32 v238, 16, v145
	v_and_b32_e32 v239, 0xffff0000, v145
	v_pk_add_f32 v[240:241], v[240:241], v[238:239] neg_lo:[0,1] neg_hi:[0,1]
	v_cvt_pk_bf16_f32 v236, v236, v237
	v_pk_fma_f32 v[238:239], v[240:241], v[248:249], v[238:239]
	s_nop 0
	v_cvt_pk_bf16_f32 v237, v238, v239
	ds_write_b128 v213, v[234:237] offset:9216
	ds_write_b128 v213, v[138:141] offset:27648
	v_lshlrev_b32_e32 v234, 16, v150
	v_and_b32_e32 v235, 0xffff0000, v150
	v_lshlrev_b32_e32 v236, 16, v154
	v_and_b32_e32 v237, 0xffff0000, v154
	v_pk_add_f32 v[236:237], v[236:237], v[234:235] neg_lo:[0,1] neg_hi:[0,1]
	s_nop 0
	v_pk_fma_f32 v[166:167], v[236:237], v[250:251], v[234:235]
	v_lshlrev_b32_e32 v234, 16, v151
	v_and_b32_e32 v235, 0xffff0000, v151
	v_lshlrev_b32_e32 v236, 16, v155
	v_and_b32_e32 v237, 0xffff0000, v155
	v_pk_add_f32 v[236:237], v[236:237], v[234:235] neg_lo:[0,1] neg_hi:[0,1]
	v_cvt_pk_bf16_f32 v166, v166, v167
	v_pk_fma_f32 v[168:169], v[236:237], v[252:253], v[234:235]
	v_lshlrev_b32_e32 v234, 16, v156
	v_cvt_pk_bf16_f32 v167, v168, v169
	v_lshlrev_b32_e32 v168, 16, v152
	v_and_b32_e32 v169, 0xffff0000, v152
	v_and_b32_e32 v235, 0xffff0000, v156
	v_pk_add_f32 v[234:235], v[234:235], v[168:169] neg_lo:[0,1] neg_hi:[0,1]
	s_nop 0
	v_pk_fma_f32 v[162:163], v[234:235], v[246:247], v[168:169]
	v_lshlrev_b32_e32 v234, 16, v157
	v_cvt_pk_bf16_f32 v168, v162, v163
	v_lshlrev_b32_e32 v162, 16, v153
	v_and_b32_e32 v163, 0xffff0000, v153
	v_and_b32_e32 v235, 0xffff0000, v157
	v_pk_add_f32 v[234:235], v[234:235], v[162:163] neg_lo:[0,1] neg_hi:[0,1]
	s_nop 0
	v_pk_fma_f32 v[162:163], v[234:235], v[248:249], v[162:163]
	s_nop 0
	v_cvt_pk_bf16_f32 v169, v162, v163
	ds_write_b128 v213, v[166:169] offset:13824
	ds_write_b128 v213, v[158:161] offset:32256
	global_load_dwordx4 v[246:249], v[194:195], off offset:512
	global_load_dwordx4 v[250:253], v[194:195], off offset:496
	s_cbranch_scc1 .Lmixpf_b_last
	global_load_dwordx4 v[114:117], v200, s[84:85] offset:512
	global_load_dwordx4 v[118:121], v186, s[86:87] offset:512
	global_load_dwordx4 v[122:125], v210, s[86:87]
	global_load_dwordx4 v[126:129], v208, s[84:85] offset:512
	global_load_dwordx4 v[130:133], v188, s[86:87] offset:512
	s_and_saveexec_b64 s[22:23], s[0:1]
	s_cbranch_execz .LBB0_687
	global_load_dwordx4 v[134:137], v206, s[86:87]
.LBB0_687:
	s_andn2_b64 exec, s[22:23], s[0:1]
	s_cbranch_execz .Lzf_12
	v_mov_b32_e32 v134, 0
	v_mov_b32_e32 v135, 0
	v_mov_b32_e32 v136, 0
	v_mov_b32_e32 v137, 0
.Lzf_12:
	s_mov_b64 exec, s[22:23]
	global_load_dwordx4 v[142:145], v204, s[84:85] offset:512
	global_load_dwordx4 v[146:149], v190, s[86:87] offset:512
	s_and_saveexec_b64 s[22:23], s[4:5]
	s_cbranch_execz .LBB0_689
	global_load_dwordx4 v[138:141], v202, s[86:87]
.LBB0_689:
	s_andn2_b64 exec, s[22:23], s[4:5]
	s_cbranch_execz .Lzf_13
	v_mov_b32_e32 v138, 0
	v_mov_b32_e32 v139, 0
	v_mov_b32_e32 v140, 0
	v_mov_b32_e32 v141, 0
.Lzf_13:
	s_mov_b64 exec, s[22:23]
	global_load_dwordx4 v[150:153], v198, s[84:85] offset:512
	global_load_dwordx4 v[154:157], v192, s[86:87] offset:512
	s_and_saveexec_b64 s[22:23], s[6:7]
	s_cbranch_execz .Lzf_14
	global_load_dwordx4 v[158:161], v196, s[86:87]
.Lzf_14:
	s_andn2_b64 exec, s[22:23], s[6:7]
	s_cbranch_execz .LBB0_673
	v_mov_b32_e32 v158, 0
	v_mov_b32_e32 v159, 0
	v_mov_b32_e32 v160, 0
	v_mov_b32_e32 v161, 0
	s_branch .LBB0_673

.LBB0_1724:
	s_cmp_gt_u32 s37, 12
	s_waitcnt vmcnt(3)
	ds_write_b128 v154, v[66:69] offset:36864
	ds_write_b128 v154, v[70:73] offset:55296
	s_waitcnt vmcnt(2)
	ds_write_b128 v154, v[78:81] offset:41472
	ds_write_b128 v154, v[74:77] offset:59904
	s_waitcnt vmcnt(1)
	ds_write_b128 v154, v[82:85] offset:46080
	ds_write_b128 v154, v[90:93] offset:64512
	s_waitcnt vmcnt(0)
	ds_write_b128 v154, v[102:105] offset:50688
	ds_write_b128 v156, v[106:109] offset:13824
	s_cbranch_scc1 .LBB0_1734
	global_load_dwordx4 v[66:69], v152, s[84:85] offset:384
	s_and_saveexec_b64 s[20:21], s[4:5]
	s_cbranch_execz .LBB0_1727
	global_load_dwordx4 v[70:73], v150, s[86:87] offset:384
.LBB0_1727:
	s_andn2_b64 exec, s[20:21], s[4:5]
	s_cbranch_execz .Lzf_15
	v_mov_b32_e32 v70, 0
	v_mov_b32_e32 v71, 0
	v_mov_b32_e32 v72, 0
	v_mov_b32_e32 v73, 0
.Lzf_15:
	s_mov_b64 exec, s[20:21]
	global_load_dwordx4 v[78:81], v148, s[84:85] offset:384
	s_and_saveexec_b64 s[20:21], s[6:7]
	s_cbranch_execz .LBB0_1729
	global_load_dwordx4 v[74:77], v146, s[86:87] offset:384
.LBB0_1729:
	s_andn2_b64 exec, s[20:21], s[6:7]
	s_cbranch_execz .Lzf_16
	v_mov_b32_e32 v74, 0
	v_mov_b32_e32 v75, 0
	v_mov_b32_e32 v76, 0
	v_mov_b32_e32 v77, 0
.Lzf_16:
	s_mov_b64 exec, s[20:21]
	v_mov_b32_e32 v131, v130
	global_load_dwordx4 v[82:85], v144, s[84:85] offset:384
	s_and_saveexec_b64 s[20:21], s[8:9]
	s_cbranch_execz .LBB0_1731
	global_load_dwordx4 v[90:93], v142, s[86:87] offset:384
.LBB0_1731:
	s_andn2_b64 exec, s[20:21], s[8:9]
	s_cbranch_execz .Lzf_17
	v_mov_b32_e32 v90, 0
	v_mov_b32_e32 v91, 0
	v_mov_b32_e32 v92, 0
	v_mov_b32_e32 v93, 0
.Lzf_17:
	s_mov_b64 exec, s[20:21]
	global_load_dwordx4 v[102:105], v140, s[84:85] offset:384
	s_and_saveexec_b64 s[20:21], s[10:11]
	s_cbranch_execz .LBB0_1733
	global_load_dwordx4 v[106:109], v138, s[86:87] offset:384
.LBB0_1733:
	s_andn2_b64 exec, s[20:21], s[10:11]
	s_cbranch_execz .Lzf_18
	v_mov_b32_e32 v106, 0
	v_mov_b32_e32 v107, 0
	v_mov_b32_e32 v108, 0
	v_mov_b32_e32 v109, 0
.Lzf_18:
	s_mov_b64 exec, s[20:21]
.LBB0_1734:
	s_cmp_gt_u32 s37, 13
	s_cselect_b64 s[20:21], -1, 0
	s_and_b64 vcc, exec, s[20:21]
	s_waitcnt lgkmcnt(4)
	v_mfma_f32_32x32x16_bf16 v[50:65], v[192:195], v[196:199], v[50:65]
	v_mfma_f32_32x32x16_bf16 v[34:49], v[192:195], v[200:203], v[34:49]
	v_mfma_f32_32x32x16_bf16 v[18:33], v[204:207], v[196:199], v[18:33]
	v_mfma_f32_32x32x16_bf16 v[2:17], v[204:207], v[200:203], v[2:17]
	ds_read_b128 v[164:167], v161 offset:64
	ds_read_b128 v[168:171], v162 offset:18496
	ds_read_b128 v[172:175], v162 offset:23104
	ds_read_b128 v[176:179], v161 offset:4672
	s_waitcnt lgkmcnt(4)
	v_mfma_f32_32x32x16_bf16 v[50:65], v[208:211], v[212:215], v[50:65]
	v_mfma_f32_32x32x16_bf16 v[34:49], v[208:211], v[216:219], v[34:49]
	v_mfma_f32_32x32x16_bf16 v[18:33], v[220:223], v[212:215], v[18:33]
	v_mfma_f32_32x32x16_bf16 v[2:17], v[220:223], v[216:219], v[2:17]
	ds_read_b128 v[180:183], v161 offset:96
	ds_read_b128 v[184:187], v162 offset:18528
	ds_read_b128 v[188:191], v162 offset:23136
	ds_read_b128 v[224:227], v161 offset:4704
	s_waitcnt lgkmcnt(4)
	v_mfma_f32_32x32x16_bf16 v[50:65], v[164:167], v[168:171], v[50:65]
	v_mfma_f32_32x32x16_bf16 v[34:49], v[164:167], v[172:175], v[34:49]
	s_waitcnt lgkmcnt(0)
	s_barrier
	ds_read_b128 v[192:195], v161 offset:36864
	ds_read_b128 v[196:199], v162 offset:55296
	ds_read_b128 v[200:203], v162 offset:59904
	ds_read_b128 v[204:207], v161 offset:41472
	ds_read_b128 v[208:211], v161 offset:36896
	ds_read_b128 v[212:215], v162 offset:55328
	ds_read_b128 v[216:219], v162 offset:59936
	ds_read_b128 v[220:223], v161 offset:41504
	v_mfma_f32_32x32x16_bf16 v[18:33], v[176:179], v[168:171], v[18:33]
	v_mfma_f32_32x32x16_bf16 v[2:17], v[176:179], v[172:175], v[2:17]
	v_mfma_f32_32x32x16_bf16 v[50:65], v[180:183], v[184:187], v[50:65]
	v_mfma_f32_32x32x16_bf16 v[34:49], v[180:183], v[188:191], v[34:49]
	v_mfma_f32_32x32x16_bf16 v[18:33], v[224:227], v[184:187], v[18:33]
	v_mfma_f32_32x32x16_bf16 v[2:17], v[224:227], v[188:191], v[2:17]
	s_cbranch_vccnz .LBB0_1723
	s_cmp_gt_u32 s37, 11
	s_waitcnt vmcnt(3)
	ds_write_b128 v154, v[86:89]
	ds_write_b128 v154, v[94:97] offset:18432
	s_waitcnt vmcnt(2)
	ds_write_b128 v154, v[110:113] offset:4608
	ds_write_b128 v154, v[98:101] offset:23040
	s_waitcnt vmcnt(1)
	ds_write_b128 v154, v[114:117] offset:9216
	ds_write_b128 v154, v[118:121] offset:27648
	s_waitcnt vmcnt(0)
	ds_write_b128 v154, v[122:125] offset:13824
	ds_write_b128 v154, v[126:129] offset:32256
	s_cbranch_scc1 .LBB0_1723
	global_load_dwordx4 v[86:89], v152, s[84:85] offset:512
	s_and_saveexec_b64 s[22:23], s[4:5]
	s_cbranch_execz .LBB0_1738
	global_load_dwordx4 v[94:97], v150, s[86:87] offset:512
.LBB0_1738:
	s_andn2_b64 exec, s[22:23], s[4:5]
	s_cbranch_execz .Lzf_19
	v_mov_b32_e32 v94, 0
	v_mov_b32_e32 v95, 0
	v_mov_b32_e32 v96, 0
	v_mov_b32_e32 v97, 0
.Lzf_19:
	s_mov_b64 exec, s[22:23]
	global_load_dwordx4 v[110:113], v148, s[84:85] offset:512
	s_and_saveexec_b64 s[22:23], s[6:7]
	s_cbranch_execz .LBB0_1740
	global_load_dwordx4 v[98:101], v146, s[86:87] offset:512
.LBB0_1740:
	s_andn2_b64 exec, s[22:23], s[6:7]
	s_cbranch_execz .Lzf_20
	v_mov_b32_e32 v98, 0
	v_mov_b32_e32 v99, 0
	v_mov_b32_e32 v100, 0
	v_mov_b32_e32 v101, 0
.Lzf_20:
	s_mov_b64 exec, s[22:23]
	v_mov_b32_e32 v131, v130
	global_load_dwordx4 v[114:117], v144, s[84:85] offset:512
	s_and_saveexec_b64 s[22:23], s[8:9]
	s_cbranch_execz .LBB0_1742
	global_load_dwordx4 v[118:121], v142, s[86:87] offset:512
.LBB0_1742:
	s_andn2_b64 exec, s[22:23], s[8:9]
	s_cbranch_execz .Lzf_21
	v_mov_b32_e32 v118, 0
	v_mov_b32_e32 v119, 0
	v_mov_b32_e32 v120, 0
	v_mov_b32_e32 v121, 0
.Lzf_21:
	s_mov_b64 exec, s[22:23]
	global_load_dwordx4 v[122:125], v140, s[84:85] offset:512
	s_and_saveexec_b64 s[22:23], s[10:11]
	s_cbranch_execz .Lzf_22
	global_load_dwordx4 v[126:129], v138, s[86:87] offset:512
.Lzf_22:
	s_andn2_b64 exec, s[22:23], s[10:11]
	s_cbranch_execz .LBB0_1722
	v_mov_b32_e32 v126, 0
	v_mov_b32_e32 v127, 0
	v_mov_b32_e32 v128, 0
	v_mov_b32_e32 v129, 0
	s_branch .LBB0_1722

.LBB0_1923:
	s_cmp_gt_u32 s35, 12
	s_waitcnt vmcnt(3)
	ds_write_b128 v137, v[66:69] offset:36864
	ds_write_b128 v137, v[70:73] offset:55296
	s_waitcnt vmcnt(2)
	ds_write_b128 v137, v[78:81] offset:41472
	ds_write_b128 v137, v[74:77] offset:59904
	s_waitcnt vmcnt(1)
	ds_write_b128 v137, v[82:85] offset:46080
	ds_write_b128 v137, v[90:93] offset:64512
	s_waitcnt vmcnt(0)
	ds_write_b128 v137, v[102:105] offset:50688
	ds_write_b128 v183, v[106:109] offset:13824
	s_cbranch_scc1 .LBB0_1933
	global_load_dwordx4 v[66:69], v180, s[84:85] offset:384
	s_and_saveexec_b64 s[2:3], s[12:13]
	s_cbranch_execz .LBB0_1926
	global_load_dwordx4 v[70:73], v178, s[86:87] offset:384
.LBB0_1926:
	s_andn2_b64 exec, s[2:3], s[12:13]
	s_cbranch_execz .Lzf_23
	v_mov_b32_e32 v70, 0
	v_mov_b32_e32 v71, 0
	v_mov_b32_e32 v72, 0
	v_mov_b32_e32 v73, 0
.Lzf_23:
	s_mov_b64 exec, s[2:3]
	global_load_dwordx4 v[78:81], v176, s[84:85] offset:384
	s_and_saveexec_b64 s[2:3], s[14:15]
	s_cbranch_execz .LBB0_1928
	global_load_dwordx4 v[74:77], v174, s[86:87] offset:384
.LBB0_1928:
	s_andn2_b64 exec, s[2:3], s[14:15]
	s_cbranch_execz .Lzf_24
	v_mov_b32_e32 v74, 0
	v_mov_b32_e32 v75, 0
	v_mov_b32_e32 v76, 0
	v_mov_b32_e32 v77, 0
.Lzf_24:
	s_mov_b64 exec, s[2:3]
	v_mov_b32_e32 v131, v130
	global_load_dwordx4 v[82:85], v172, s[84:85] offset:384
	s_and_saveexec_b64 s[2:3], s[16:17]
	s_cbranch_execz .LBB0_1930
	global_load_dwordx4 v[90:93], v170, s[86:87] offset:384
.LBB0_1930:
	s_andn2_b64 exec, s[2:3], s[16:17]
	s_cbranch_execz .Lzf_25
	v_mov_b32_e32 v90, 0
	v_mov_b32_e32 v91, 0
	v_mov_b32_e32 v92, 0
	v_mov_b32_e32 v93, 0
.Lzf_25:
	s_mov_b64 exec, s[2:3]
	global_load_dwordx4 v[102:105], v168, s[84:85] offset:384
	s_and_saveexec_b64 s[2:3], s[18:19]
	s_cbranch_execz .LBB0_1932
	global_load_dwordx4 v[106:109], v166, s[86:87] offset:384
.LBB0_1932:
	s_andn2_b64 exec, s[2:3], s[18:19]
	s_cbranch_execz .Lzf_26
	v_mov_b32_e32 v106, 0
	v_mov_b32_e32 v107, 0
	v_mov_b32_e32 v108, 0
	v_mov_b32_e32 v109, 0

.LBB0_1933:
	s_cmp_gt_u32 s35, 13
	s_cselect_b64 s[2:3], -1, 0
	s_and_b64 vcc, exec, s[2:3]
	s_waitcnt lgkmcnt(4)
	v_mfma_f32_32x32x16_bf16 v[50:65], v[206:209], v[210:213], v[50:65]
	v_mfma_f32_32x32x16_bf16 v[34:49], v[206:209], v[214:217], v[34:49]
	v_mfma_f32_32x32x16_bf16 v[18:33], v[218:221], v[210:213], v[18:33]
	v_mfma_f32_32x32x16_bf16 v[2:17], v[218:221], v[214:217], v[2:17]
	ds_read_b128 v[206:209], v203 offset:64
	ds_read_b128 v[210:213], v204 offset:18496
	ds_read_b128 v[214:217], v204 offset:23104
	ds_read_b128 v[218:221], v203 offset:4672
	s_waitcnt lgkmcnt(4)
	v_mfma_f32_32x32x16_bf16 v[50:65], v[222:225], v[226:229], v[50:65]
	v_mfma_f32_32x32x16_bf16 v[34:49], v[222:225], v[230:233], v[34:49]
	v_mfma_f32_32x32x16_bf16 v[18:33], v[234:237], v[226:229], v[18:33]
	v_mfma_f32_32x32x16_bf16 v[2:17], v[234:237], v[230:233], v[2:17]
	ds_read_b128 v[222:225], v203 offset:96
	ds_read_b128 v[226:229], v204 offset:18528
	ds_read_b128 v[230:233], v204 offset:23136
	ds_read_b128 v[234:237], v203 offset:4704
	s_waitcnt lgkmcnt(4)
	v_mfma_f32_32x32x16_bf16 v[50:65], v[206:209], v[210:213], v[50:65]
	v_mfma_f32_32x32x16_bf16 v[34:49], v[206:209], v[214:217], v[34:49]
	s_waitcnt lgkmcnt(0)
	s_barrier
	v_mfma_f32_32x32x16_bf16 v[18:33], v[218:221], v[210:213], v[18:33]
	v_mfma_f32_32x32x16_bf16 v[2:17], v[218:221], v[214:217], v[2:17]
	ds_read_b128 v[206:209], v203 offset:36864
	ds_read_b128 v[210:213], v204 offset:55296
	ds_read_b128 v[214:217], v204 offset:59904
	ds_read_b128 v[218:221], v203 offset:41472
	v_mfma_f32_32x32x16_bf16 v[50:65], v[222:225], v[226:229], v[50:65]
	v_mfma_f32_32x32x16_bf16 v[34:49], v[222:225], v[230:233], v[34:49]
	v_mfma_f32_32x32x16_bf16 v[18:33], v[234:237], v[226:229], v[18:33]
	v_mfma_f32_32x32x16_bf16 v[2:17], v[234:237], v[230:233], v[2:17]
	ds_read_b128 v[222:225], v203 offset:36896
	ds_read_b128 v[226:229], v204 offset:55328
	ds_read_b128 v[230:233], v204 offset:59936
	ds_read_b128 v[234:237], v203 offset:41504
	s_cbranch_vccnz .LBB0_1922
	s_cmp_gt_u32 s35, 11
	s_waitcnt vmcnt(3)
	ds_write_b128 v137, v[86:89]
	ds_write_b128 v137, v[94:97] offset:18432
	s_waitcnt vmcnt(2)
	ds_write_b128 v137, v[110:113] offset:4608
	ds_write_b128 v137, v[98:101] offset:23040
	s_waitcnt vmcnt(1)
	ds_write_b128 v137, v[114:117] offset:9216
	ds_write_b128 v137, v[118:121] offset:27648
	s_waitcnt vmcnt(0)
	ds_write_b128 v137, v[122:125] offset:13824
	ds_write_b128 v137, v[126:129] offset:32256
	s_cbranch_scc1 .LBB0_1922
	global_load_dwordx4 v[86:89], v180, s[84:85] offset:512
	s_and_saveexec_b64 s[36:37], s[12:13]
	s_cbranch_execz .LBB0_1937
	global_load_dwordx4 v[94:97], v178, s[86:87] offset:512
.LBB0_1937:
	s_andn2_b64 exec, s[36:37], s[12:13]
	s_cbranch_execz .Lzf_27
	v_mov_b32_e32 v94, 0
	v_mov_b32_e32 v95, 0
	v_mov_b32_e32 v96, 0
	v_mov_b32_e32 v97, 0
.Lzf_27:
	s_mov_b64 exec, s[36:37]
	global_load_dwordx4 v[110:113], v176, s[84:85] offset:512
	s_and_saveexec_b64 s[36:37], s[14:15]
	s_cbranch_execz .LBB0_1939
	global_load_dwordx4 v[98:101], v174, s[86:87] offset:512
.LBB0_1939:
	s_andn2_b64 exec, s[36:37], s[14:15]
	s_cbranch_execz .Lzf_28
	v_mov_b32_e32 v98, 0
	v_mov_b32_e32 v99, 0
	v_mov_b32_e32 v100, 0
	v_mov_b32_e32 v101, 0
.Lzf_28:
	s_mov_b64 exec, s[36:37]
	v_mov_b32_e32 v131, v130
	global_load_dwordx4 v[114:117], v172, s[84:85] offset:512
	s_and_saveexec_b64 s[36:37], s[16:17]
	s_cbranch_execz .LBB0_1941
	global_load_dwordx4 v[118:121], v170, s[86:87] offset:512
.LBB0_1941:
	s_andn2_b64 exec, s[36:37], s[16:17]
	s_cbranch_execz .Lzf_29
	v_mov_b32_e32 v118, 0
	v_mov_b32_e32 v119, 0
	v_mov_b32_e32 v120, 0
	v_mov_b32_e32 v121, 0
.Lzf_29:
	s_mov_b64 exec, s[36:37]
	global_load_dwordx4 v[122:125], v168, s[84:85] offset:512
	s_and_saveexec_b64 s[36:37], s[18:19]
	s_cbranch_execz .Lzf_30
	global_load_dwordx4 v[126:129], v166, s[86:87] offset:512
.Lzf_30:
	s_andn2_b64 exec, s[36:37], s[18:19]
	s_cbranch_execz .LBB0_1921
	v_mov_b32_e32 v126, 0
	v_mov_b32_e32 v127, 0
	v_mov_b32_e32 v128, 0
	v_mov_b32_e32 v129, 0
	s_branch .LBB0_1921

.LBB0_2253:
	s_cmp_gt_u32 s13, 12
	s_waitcnt vmcnt(5)
	ds_write_b128 v160, v[66:69] offset:36864
	s_waitcnt vmcnt(4)
	ds_write_b128 v160, v[70:73] offset:55296
	s_waitcnt vmcnt(3)
	ds_write_b128 v160, v[74:77] offset:41472
	s_waitcnt vmcnt(2)
	ds_write_b128 v160, v[78:81] offset:59904
	s_waitcnt vmcnt(1)
	ds_write_b128 v160, v[82:85] offset:46080
	ds_write_b128 v160, v[86:89] offset:64512
	s_waitcnt vmcnt(0)
	ds_write_b128 v160, v[102:105] offset:50688
	ds_write_b128 v161, v[114:117] offset:13824
	s_cbranch_scc1 .LBB0_2259
	global_load_dwordx4 v[66:69], v158, s[84:85] offset:384
	global_load_dwordx4 v[70:73], v156, s[86:87] offset:384
	v_mov_b32_e32 v131, v130
	global_load_dwordx4 v[74:77], v154, s[84:85] offset:384
	global_load_dwordx4 v[78:81], v152, s[86:87] offset:384
	global_load_dwordx4 v[82:85], v150, s[84:85] offset:384
	s_and_saveexec_b64 s[2:3], s[6:7]
	s_cbranch_execz .LBB0_2256
	global_load_dwordx4 v[86:89], v148, s[86:87] offset:384
.LBB0_2256:
	s_andn2_b64 exec, s[2:3], s[6:7]
	s_cbranch_execz .Lzf_31
	v_mov_b32_e32 v86, 0
	v_mov_b32_e32 v87, 0
	v_mov_b32_e32 v88, 0
	v_mov_b32_e32 v89, 0
.Lzf_31:
	s_mov_b64 exec, s[2:3]
	global_load_dwordx4 v[102:105], v146, s[84:85] offset:384
	s_and_saveexec_b64 s[2:3], s[8:9]
	s_cbranch_execz .LBB0_2258
	global_load_dwordx4 v[114:117], v144, s[86:87] offset:384
.LBB0_2258:
	s_andn2_b64 exec, s[2:3], s[8:9]
	s_cbranch_execz .Lzf_32
	v_mov_b32_e32 v114, 0
	v_mov_b32_e32 v115, 0
	v_mov_b32_e32 v116, 0
	v_mov_b32_e32 v117, 0

.LBB0_2259:
	s_cmp_gt_u32 s13, 13
	s_cselect_b64 s[2:3], -1, 0
	s_and_b64 vcc, exec, s[2:3]
	s_waitcnt lgkmcnt(4)
	v_mfma_f32_32x32x16_bf16 v[50:65], v[212:215], v[216:219], v[50:65]
	v_mfma_f32_32x32x16_bf16 v[34:49], v[220:223], v[216:219], v[34:49]
	v_mfma_f32_32x32x16_bf16 v[18:33], v[212:215], v[224:227], v[18:33]
	v_mfma_f32_32x32x16_bf16 v[2:17], v[220:223], v[224:227], v[2:17]
	ds_read_b128 v[184:187], v182 offset:18496
	ds_read_b128 v[188:191], v162 offset:64
	ds_read_b128 v[192:195], v182 offset:23104
	ds_read_b128 v[196:199], v162 offset:4672
	s_waitcnt lgkmcnt(4)
	v_mfma_f32_32x32x16_bf16 v[50:65], v[228:231], v[232:235], v[50:65]
	v_mfma_f32_32x32x16_bf16 v[34:49], v[236:239], v[232:235], v[34:49]
	v_mfma_f32_32x32x16_bf16 v[18:33], v[228:231], v[240:243], v[18:33]
	v_mfma_f32_32x32x16_bf16 v[2:17], v[236:239], v[240:243], v[2:17]
	ds_read_b128 v[200:203], v182 offset:18528
	ds_read_b128 v[204:207], v162 offset:96
	ds_read_b128 v[208:211], v182 offset:23136
	ds_read_b128 v[248:251], v162 offset:4704
	s_waitcnt lgkmcnt(4)
	v_mfma_f32_32x32x16_bf16 v[50:65], v[184:187], v[188:191], v[50:65]
	v_mfma_f32_32x32x16_bf16 v[34:49], v[192:195], v[188:191], v[34:49]
	s_waitcnt lgkmcnt(0)
	s_barrier
	ds_read_b128 v[212:215], v182 offset:55296
	ds_read_b128 v[216:219], v162 offset:36864
	ds_read_b128 v[220:223], v182 offset:59904
	ds_read_b128 v[224:227], v162 offset:41472
	ds_read_b128 v[228:231], v182 offset:55328
	ds_read_b128 v[232:235], v162 offset:36896
	ds_read_b128 v[236:239], v182 offset:59936
	ds_read_b128 v[240:243], v162 offset:41504
	v_mfma_f32_32x32x16_bf16 v[18:33], v[184:187], v[196:199], v[18:33]
	v_mfma_f32_32x32x16_bf16 v[2:17], v[192:195], v[196:199], v[2:17]
	v_mfma_f32_32x32x16_bf16 v[50:65], v[200:203], v[204:207], v[50:65]
	v_mfma_f32_32x32x16_bf16 v[34:49], v[208:211], v[204:207], v[34:49]
	v_mfma_f32_32x32x16_bf16 v[18:33], v[200:203], v[248:251], v[18:33]
	v_mfma_f32_32x32x16_bf16 v[2:17], v[208:211], v[248:251], v[2:17]
	s_cbranch_vccnz .LBB0_2252
	s_cmp_gt_u32 s13, 11
	s_waitcnt vmcnt(5)
	ds_write_b128 v160, v[90:93]
	s_waitcnt vmcnt(4)
	ds_write_b128 v160, v[94:97] offset:18432
	s_waitcnt vmcnt(3)
	ds_write_b128 v160, v[98:101] offset:4608
	s_waitcnt vmcnt(2)
	ds_write_b128 v160, v[106:109] offset:23040
	s_waitcnt vmcnt(1)
	ds_write_b128 v160, v[110:113] offset:9216
	ds_write_b128 v160, v[118:121] offset:27648
	s_waitcnt vmcnt(0)
	ds_write_b128 v160, v[122:125] offset:13824
	ds_write_b128 v160, v[126:129] offset:32256
	s_cbranch_scc1 .LBB0_2252
	global_load_dwordx4 v[90:93], v158, s[84:85] offset:512
	global_load_dwordx4 v[94:97], v156, s[86:87] offset:512
	v_mov_b32_e32 v131, v130
	global_load_dwordx4 v[98:101], v154, s[84:85] offset:512
	global_load_dwordx4 v[106:109], v152, s[86:87] offset:512
	global_load_dwordx4 v[110:113], v150, s[84:85] offset:512
	s_and_saveexec_b64 s[14:15], s[6:7]
	s_cbranch_execz .LBB0_2263
	global_load_dwordx4 v[118:121], v148, s[86:87] offset:512
.LBB0_2263:
	s_andn2_b64 exec, s[14:15], s[6:7]
	s_cbranch_execz .Lzf_33
	v_mov_b32_e32 v118, 0
	v_mov_b32_e32 v119, 0
	v_mov_b32_e32 v120, 0
	v_mov_b32_e32 v121, 0
.Lzf_33:
	s_mov_b64 exec, s[14:15]
	global_load_dwordx4 v[122:125], v146, s[84:85] offset:512
	s_and_saveexec_b64 s[14:15], s[8:9]
	s_cbranch_execz .Lzf_34
	global_load_dwordx4 v[126:129], v144, s[86:87] offset:512
.Lzf_34:
	s_andn2_b64 exec, s[14:15], s[8:9]
	s_cbranch_execz .LBB0_2251
	v_mov_b32_e32 v126, 0
	v_mov_b32_e32 v127, 0
	v_mov_b32_e32 v128, 0
	v_mov_b32_e32 v129, 0
	s_branch .LBB0_2251

.LBB0_2925:
	s_cmp_gt_u32 s37, 28
	s_waitcnt vmcnt(3)
	ds_write_b128 v154, v[66:69] offset:36864
	ds_write_b128 v154, v[70:73] offset:55296
	s_waitcnt vmcnt(2)
	ds_write_b128 v154, v[78:81] offset:41472
	ds_write_b128 v154, v[74:77] offset:59904
	s_waitcnt vmcnt(1)
	ds_write_b128 v154, v[82:85] offset:46080
	ds_write_b128 v154, v[90:93] offset:64512
	s_waitcnt vmcnt(0)
	ds_write_b128 v154, v[102:105] offset:50688
	ds_write_b128 v156, v[106:109] offset:13824
	s_cbranch_scc1 .LBB0_2935
	global_load_dwordx4 v[66:69], v152, s[84:85] offset:384
	s_and_saveexec_b64 s[20:21], s[4:5]
	s_cbranch_execz .LBB0_2928
	global_load_dwordx4 v[70:73], v150, s[86:87] offset:384

.LBB0_2935:
	s_cmp_gt_u32 s37, 29
	s_cselect_b64 s[20:21], -1, 0
	s_and_b64 vcc, exec, s[20:21]
	s_waitcnt lgkmcnt(4)
	v_mfma_f32_32x32x16_bf16 v[50:65], v[192:195], v[196:199], v[50:65]
	v_mfma_f32_32x32x16_bf16 v[34:49], v[192:195], v[200:203], v[34:49]
	v_mfma_f32_32x32x16_bf16 v[18:33], v[204:207], v[196:199], v[18:33]
	v_mfma_f32_32x32x16_bf16 v[2:17], v[204:207], v[200:203], v[2:17]
	ds_read_b128 v[164:167], v161 offset:64
	ds_read_b128 v[168:171], v162 offset:18496
	ds_read_b128 v[172:175], v162 offset:23104
	ds_read_b128 v[176:179], v161 offset:4672
	s_waitcnt lgkmcnt(4)
	v_mfma_f32_32x32x16_bf16 v[50:65], v[208:211], v[212:215], v[50:65]
	v_mfma_f32_32x32x16_bf16 v[34:49], v[208:211], v[216:219], v[34:49]
	v_mfma_f32_32x32x16_bf16 v[18:33], v[220:223], v[212:215], v[18:33]
	v_mfma_f32_32x32x16_bf16 v[2:17], v[220:223], v[216:219], v[2:17]
	ds_read_b128 v[180:183], v161 offset:96
	ds_read_b128 v[184:187], v162 offset:18528
	ds_read_b128 v[188:191], v162 offset:23136
	ds_read_b128 v[224:227], v161 offset:4704
	s_waitcnt lgkmcnt(4)
	v_mfma_f32_32x32x16_bf16 v[50:65], v[164:167], v[168:171], v[50:65]
	v_mfma_f32_32x32x16_bf16 v[34:49], v[164:167], v[172:175], v[34:49]
	s_waitcnt lgkmcnt(0)
	s_barrier
	ds_read_b128 v[192:195], v161 offset:36864
	ds_read_b128 v[196:199], v162 offset:55296
	ds_read_b128 v[200:203], v162 offset:59904
	ds_read_b128 v[204:207], v161 offset:41472
	ds_read_b128 v[208:211], v161 offset:36896
	ds_read_b128 v[212:215], v162 offset:55328
	ds_read_b128 v[216:219], v162 offset:59936
	ds_read_b128 v[220:223], v161 offset:41504
	v_mfma_f32_32x32x16_bf16 v[18:33], v[176:179], v[168:171], v[18:33]
	v_mfma_f32_32x32x16_bf16 v[2:17], v[176:179], v[172:175], v[2:17]
	v_mfma_f32_32x32x16_bf16 v[50:65], v[180:183], v[184:187], v[50:65]
	v_mfma_f32_32x32x16_bf16 v[34:49], v[180:183], v[188:191], v[34:49]
	v_mfma_f32_32x32x16_bf16 v[18:33], v[224:227], v[184:187], v[18:33]
	v_mfma_f32_32x32x16_bf16 v[2:17], v[224:227], v[188:191], v[2:17]
	s_cbranch_vccnz .LBB0_2924
	s_cmp_gt_u32 s37, 27
	s_waitcnt vmcnt(3)
	ds_write_b128 v154, v[86:89]
	ds_write_b128 v154, v[94:97] offset:18432
	s_waitcnt vmcnt(2)
	ds_write_b128 v154, v[110:113] offset:4608
	ds_write_b128 v154, v[98:101] offset:23040
	s_waitcnt vmcnt(1)
	ds_write_b128 v154, v[114:117] offset:9216
	ds_write_b128 v154, v[118:121] offset:27648
	s_waitcnt vmcnt(0)
	ds_write_b128 v154, v[122:125] offset:13824
	ds_write_b128 v154, v[126:129] offset:32256
	s_cbranch_scc1 .LBB0_2924
	global_load_dwordx4 v[86:89], v152, s[84:85] offset:512
	s_and_saveexec_b64 s[22:23], s[4:5]
	s_cbranch_execz .LBB0_2939
	global_load_dwordx4 v[94:97], v150, s[86:87] offset:512
